# odd workgroups start the in-projection and up-GEMM phases 4 us late (de-phases the lockstep epilogue store bursts) on top of the GQA reschedule
# speedup vs baseline: 1.0102x; 1.0011x over previous
; #define PG8_BAR __builtin_amdgcn_s_barrier()
;     int tid_ = threadIdx.x; asm volatile("" : "+v"(tid_));
;     const int tid = tid_, wid = __builtin_amdgcn_readfirstlane(tid >> 6), lane = tid & 63, wr = wid >> 2, wc = wid & 3, fr = lane & 15, fq = lane >> 4;
;     const int K = g.K, nt = K / BK, lda = g.lda;
;     unsigned voffA[2], voffB[2];
; #pragma unroll
;     for (int i = 0; i < 2; ++i) { int R, C; stage_rc(tid * 16 + i * 8192, R, C); const int Rb = Epi::PERM ? ((R & ~31) + perm32(R & 31)) : R;
;         voffA[i] = (unsigned)(R * lda + C) * 2u; voffB[i] = (unsigned)(Rb * K + C) * 2u; }
;     const size_t kstep = (size_t)(BK * 2);
;     const size_t hstepA = (size_t)HALF * lda * 2, hstepB = (size_t)HALF * K * 2, tstepA = 2 * hstepA, tstepB = 2 * hstepB;
;     const unsigned ldsw = (unsigned)wid * 1024u;
;     const int aoff = lds_byte(wr * 64 + fr, fq * 8), boff = lds_byte(wc * 32 + fr, fq * 8);
;     ...
;     Unit cur, nxt; int ui = 0;
;     if (!S.next(0, cur)) return;
;     f32x4 acc[2][2][4][2];
; #pragma unroll
;     for (int a = 0; a < 2; ++a)
; #pragma unroll
;         for (int b = 0; b < 2; ++b)
; #pragma unroll
;             for (int m = 0; m < 4; ++m)
; #pragma unroll
;                 for (int n = 0; n < 2; ++n) acc[a][b][m][n] = (f32x4){0.f, 0.f, 0.f, 0.f};
;     i32x8 At[4], B0[2], B1[2];
;     int scl_w = 0x7f7f7f7f - W8_SHIFT * 0x01010101, scl_x = 0x7f7f7f7f - g.xshift * 0x01010101; asm volatile("" : "+v"(scl_w), "+v"(scl_x)); (void)scl_w; (void)scl_x;
;     const char* cA = (const char*)g.A + (size_t)cur.pm * tstepA; const char* cB = (const char*)g.Bt + (size_t)cur.pn * tstepB;
;     PG8_STAGE(PG8_SB(0, 0), cB, voffB); PG8_STAGE(PG8_SB(0, 1), cB + hstepB, voffB); PG8_STAGE(PG8_SA(0, 0), cA, voffA); PG8_STAGE(PG8_SA(0, 1), cA + hstepA, voffA);
;     if (wr == 1) PG8_BAR;
;     PG8_WAIT_V(2); PG8_BAR;
;     PG8_STAGE(PG8_SB(1, 0), cB + kstep, voffB); PG8_STAGE(PG8_SA(1, 0), cA + kstep, voffA); PG8_STAGE(PG8_SB(1, 1), cB + hstepB + kstep, voffB);
;     PG8_WAIT_V(6); PG8_BAR;
; __global__ void __launch_bounds__(NWAVES * 64, 2) mega_fwd(Args args) {
;     ...
;             { pg8::Gemm g{(const bf16_t*)(XN8 + (size_t)row0 * DM), (const bf16_t*)Win8, CR, 4608, DM / 2, DM / 2, 0}; pg8::StaticOrder S; S.init(CR, 4608, G, bx);
;               pg8::EpiB E{Z, 0, 1, nullptr, 0, 0};
;               _Pragma("unroll 1") for (int rep = 0; rep <= DUP_A; ++rep)
.LBB0_176:
	s_and_b64 s[2:3], s[44:45], exec
	s_mov_b32 s2, 0x8000
	s_cselect_b32 s2, s2, 0x4000
	v_readlane_b32 s4, v248, 0
	v_writelane_b32 v247, s2, 53
	v_readlane_b32 s6, v248, 2
	v_readlane_b32 s7, v248, 3
	s_mov_b64 s[2:3], s[6:7]
	v_readlane_b32 s6, v247, 35
	v_readlane_b32 s5, v248, 1
	s_cmp_ge_i32 s6, s2
	s_cselect_b64 s[4:5], -1, 0
	s_cmp_lt_i32 s6, s3
	s_cselect_b64 s[2:3], -1, 0
	s_and_b64 s[2:3], s[4:5], s[2:3]
	s_andn2_b64 vcc, exec, s[2:3]
	v_writelane_b32 v247, s44, 54
	s_nop 1
	v_writelane_b32 v247, s45, 55
	s_cbranch_vccnz .LBB0_233
	v_readlane_b32 s2, v248, 8
	s_and_b32 s2, s2, 1
	s_cmp_eq_u32 s2, 0
	s_cbranch_scc1 .Ldesync_skip_a
	s_mul_i32 s6, s2, 0x190
	s_memrealtime s[2:3]
	s_waitcnt lgkmcnt(0)
	s_add_u32 s6, s2, s6
.Ldesync_spin_a:
	s_sleep 4
	s_memrealtime s[2:3]
	s_waitcnt lgkmcnt(0)
	s_sub_u32 s7, s2, s6
	s_cmp_lt_i32 s7, 0
	s_cbranch_scc1 .Ldesync_spin_a
.Ldesync_skip_a:
	v_readlane_b32 s2, v248, 4
	v_readlane_b32 s3, v248, 5
	v_mov_b32_e32 v0, v214
	s_load_dwordx2 s[6:7], s[2:3], 0xb0
	v_readlane_b32 s2, v247, 53
	v_mov_b32_e32 v15, v214
	s_waitcnt lgkmcnt(0)
	s_add_u32 s33, s6, 0x17300000
	s_addc_u32 s34, s7, 0
	s_lshr_b32 s35, s2, 8
	s_and_b64 s[2:3], s[44:45], exec
	s_movk_i32 s2, 0x900
	s_cselect_b32 s16, s2, 0x480
	v_readlane_b32 s2, v248, 8
	s_cmp_lt_i32 s2, s16
	v_readfirstlane_b32 s2, v15
	s_cbranch_scc0 .LBB0_201
	v_lshlrev_b32_e32 v2, 4, v15
	v_add_u32_e32 v3, 0x2000, v2
	v_ashrrev_i32_e32 v0, 31, v3
	v_lshrrev_b32_e32 v0, 22, v0
	v_add_u32_e32 v0, v3, v0
	v_ashrrev_i32_e32 v0, 10, v0
	v_mul_i32_i24_e32 v4, 0x400, v0
	v_sub_u32_e32 v3, v3, v4
	v_lshrrev_b32_e32 v4, 4, v3
	v_bitop3_b32 v3, v4, v3, 32 bitop3:0x6c
	s_add_u32 s42, s6, 0x100000
	v_readlane_b32 s3, v247, 44
	v_ashrrev_i32_e32 v4, 31, v3
	s_addc_u32 s43, s7, 0
	s_lshl_b32 s3, s3, 26
	v_lshrrev_b32_e32 v4, 26, v4
	s_add_u32 s3, s6, s3
	v_add_u32_e32 v4, v3, v4
	v_lshlrev_b32_e32 v5, 3, v0
	s_addc_u32 s8, s7, 0
	v_ashrrev_i32_e32 v10, 6, v4
	v_and_b32_e32 v5, -16, v5
	s_add_u32 s44, s3, 0xe300000
	v_add_u32_e32 v5, v10, v5
	s_addc_u32 s45, s8, 0
	v_and_b32_e32 v6, 3, v10
	s_mov_b32 s8, 0x1fffe0
	v_lshrrev_b32_e32 v7, 2, v5
	v_lshlrev_b32_e32 v8, 1, v5
	v_and_b32_e32 v4, 0xc0, v4
	v_and_or_b32 v6, v5, s8, v6
	v_and_b32_e32 v7, 4, v7
	v_and_b32_e32 v8, 24, v8
	v_sub_u32_e32 v3, v3, v4
	v_or3_b32 v6, v6, v7, v8
	v_lshlrev_b32_e32 v7, 5, v0
	v_ashrrev_i16_sdwa v3, v217, sext(v3) dst_sel:DWORD dst_unused:UNUSED_PAD src0_sel:DWORD src1_sel:BYTE_0
	v_and_b32_e32 v7, 32, v7
	v_bfe_i32 v11, v3, 0, 16
	v_add_lshl_u32 v3, v7, v11, 1
	v_lshl_add_u32 v162, v6, 11, v3
	v_lshl_add_u32 v164, v5, 11, v3
	v_bfe_i32 v3, v15, 27, 1
	v_lshrrev_b32_e32 v3, 22, v3
	v_add_u32_e32 v3, v2, v3
	v_and_b32_e32 v3, 0xfffffc00, v3
	v_sub_u32_e32 v2, v2, v3
	v_lshrrev_b32_e32 v3, 4, v2
	v_ashrrev_i32_e32 v4, 31, v15
	v_bitop3_b32 v2, v3, v2, 32 bitop3:0x6c
	v_lshrrev_b32_e32 v4, 26, v4
	v_ashrrev_i32_e32 v3, 31, v2
	v_add_u32_e32 v4, v15, v4
	v_lshrrev_b32_e32 v3, 26, v3
	v_ashrrev_i32_e32 v13, 6, v4
	v_add_u32_e32 v3, v2, v3
	v_lshlrev_b32_e32 v4, 3, v13
	v_ashrrev_i32_e32 v12, 6, v3
	v_and_b32_e32 v4, -16, v4
	v_add_u32_e32 v4, v12, v4
	v_and_b32_e32 v5, 3, v12
	s_lshr_b32 s46, s16, 3
	v_and_or_b32 v5, v4, s8, v5
	v_readlane_b32 s8, v247, 38
	s_or_b32 s8, s46, s8
	v_readlane_b32 s9, v247, 37
	s_mul_i32 s8, s8, s9
	v_readlane_b32 s9, v248, 13
	s_add_i32 s8, s8, s9
	s_mul_hi_i32 s9, s8, 0x38e38e39
	s_lshr_b32 s11, s9, 31
	s_ashr_i32 s9, s9, 5
	s_add_i32 s9, s9, s11
	s_lshl_b32 s11, s9, 3
	v_and_b32_e32 v3, 0xc0, v3
	s_sub_i32 s12, s35, s11
	v_sub_u32_e32 v2, v2, v3
	s_min_i32 s12, s12, 8
	v_ashrrev_i16_sdwa v2, v217, sext(v2) dst_sel:DWORD dst_unused:UNUSED_PAD src0_sel:DWORD src1_sel:BYTE_0
	s_abs_i32 s13, s12
	v_bfe_i32 v14, v2, 0, 16
	v_cvt_f32_u32_e32 v2, s13
	s_sub_i32 s15, 0, s13
	s_mulk_i32 s9, 0x90
	s_sub_i32 s8, s8, s9
	v_rcp_iflag_f32_e32 v2, v2
	s_abs_i32 s14, s8
	s_ashr_i32 s3, s2, 6
	s_xor_b32 s9, s8, s12
	v_mul_f32_e32 v2, 0x4f7ffffe, v2
	v_cvt_u32_f32_e32 v2, v2
	s_ashr_i32 s10, s2, 8
	s_lshl_b32 s47, s3, 10
	s_ashr_i32 s9, s9, 31
	v_readfirstlane_b32 s18, v2
	s_mul_i32 s15, s15, s18
	s_mul_hi_u32 s15, s18, s15
	s_add_i32 s18, s18, s15
	s_mul_hi_u32 s15, s14, s18
	s_mul_i32 s18, s15, s13
	s_sub_i32 s14, s14, s18
	s_add_i32 s18, s15, 1
	s_sub_i32 s19, s14, s13
	s_cmp_ge_u32 s14, s13
	s_cselect_b32 s15, s18, s15
	s_cselect_b32 s14, s19, s14
	s_add_i32 s18, s15, 1
	s_cmp_ge_u32 s14, s13
	s_cselect_b32 s13, s18, s15
	s_xor_b32 s13, s13, s9
	s_sub_i32 s26, s13, s9
	s_mul_i32 s9, s26, s12
	s_sub_i32 s8, s8, s9
	v_lshrrev_b32_e32 v6, 2, v4
	v_lshlrev_b32_e32 v7, 1, v4
	s_add_i32 s24, s11, s8
	v_and_b32_e32 v6, 4, v6
	v_and_b32_e32 v7, 24, v7
	s_ashr_i32 s25, s24, 31
	s_ashr_i32 s27, s26, 31
	v_or3_b32 v5, v5, v6, v7
	v_lshlrev_b32_e32 v6, 5, v13
	s_lshl_b64 s[8:9], s[24:25], 19
	s_lshl_b64 s[12:13], s[26:27], 19
	v_and_b32_e32 v6, 32, v6
	s_add_u32 s30, s42, s12
	v_add_lshl_u32 v3, v6, v14, 1
	s_addc_u32 s31, s43, s13
	s_add_i32 s25, s47, 0
	v_lshl_add_u32 v166, v5, 11, v3
	v_mov_b32_e32 v184, 0x7a7a7a7a
	v_mov_b32_e32 v185, 0x7f7f7f7f
	s_add_i32 m0, s25, 0x10000
	v_lshl_add_u32 v168, v4, 11, v3
	global_load_lds_dwordx4 v166, s[30:31]
	s_add_i32 m0, s25, 0x12000
	s_add_u32 s12, s30, 0x40000
	global_load_lds_dwordx4 v162, s[30:31]
	s_addc_u32 s13, s31, 0
	s_add_i32 m0, s25, 0x14000
	v_mov_b32_e32 v167, v1
	global_load_lds_dwordx4 v166, s[12:13]
	s_add_i32 m0, s25, 0x16000
	s_add_u32 s28, s44, s8
	s_addc_u32 s29, s45, s9
	s_add_i32 s27, s25, 0x2000
	global_load_lds_dwordx4 v162, s[12:13]
	s_mov_b32 m0, s25
	s_add_u32 s8, s28, 0x40000
	global_load_lds_dwordx4 v168, s[28:29]
	s_mov_b32 m0, s27
	s_addc_u32 s9, s29, 0
	s_add_i32 s48, s25, 0x4000
	global_load_lds_dwordx4 v164, s[28:29]
	s_mov_b32 m0, s48
	s_add_i32 s49, s25, 0x6000
	global_load_lds_dwordx4 v168, s[8:9]
	s_mov_b32 m0, s49
	v_mov_b32_e32 v163, v1
	global_load_lds_dwordx4 v164, s[8:9]
	v_mov_b32_e32 v169, v1
	v_mov_b32_e32 v165, v1
	s_cmp_eq_u32 s10, 1
	v_lshl_add_u64 v[8:9], s[30:31], 0, v[166:167]
	v_lshl_add_u64 v[6:7], s[30:31], 0, v[162:163]
	v_lshl_add_u64 v[2:3], s[28:29], 0, v[168:169]
	s_cselect_b64 s[8:9], -1, 0
	s_cmp_lg_u32 s10, 1
	v_lshl_add_u64 v[4:5], s[28:29], 0, v[164:165]
	s_cbranch_scc1 .LBB0_180
	s_barrier

; __global__ void __launch_bounds__(NWAVES * 64, 2) mega_fwd(Args args) {
;     ...
;         if (PHON(9) && RUN()) { PP
;             pg8::Gemm g{XB + (size_t)row0 * DM, Wup_t, CR, DFF, DM, DM, 0}; pg8::StaticOrder S; S.init(CR, DFF, G, bx);
;             pg8::EpiB E{HB, DFF, 0, ss2 + row0, 1};
;             _Pragma("unroll 1") for (int rep = 0; rep <= DUP_I; ++rep)
;             pg8::gemm_phase<pg8::EpiB, pg8::StaticOrder>(L, g, S, E);
.LBB0_1062:
	v_readlane_b32 s12, v248, 8
	s_and_b32 s12, s12, 1
	s_cmp_eq_u32 s12, 0
	s_cbranch_scc1 .Ldesync_skip_i
	s_mul_i32 s14, s12, 0x190
	s_memrealtime s[12:13]
	s_waitcnt lgkmcnt(0)
	s_add_u32 s14, s12, s14
.Ldesync_spin_i:
	s_sleep 4
	s_memrealtime s[12:13]
	s_waitcnt lgkmcnt(0)
	s_sub_u32 s15, s12, s14
	s_cmp_lt_i32 s15, 0
	s_cbranch_scc1 .Ldesync_spin_i
